# GEMM K-loop: per-cluster s_setprio flips replaced by one static raise for waves 4-7
# speedup vs baseline: 1.0572x; 1.0053x over previous
; #define PG8_STAGE(bufoff, gbase, voff) do { _Pragma("unroll") for (int _i = 0; _i < 2; ++_i) \
;         __builtin_amdgcn_global_load_lds((const unsigned*)((const char*)(gbase) + (voff)[_i]), (PG8_LAS unsigned*)(lds + (bufoff) + ldsw + _i * 8192), 16, 0, 0); } while (0)
; #define PG8_LDA(dst, b, h) do { _Pragma("unroll") for (int m = 0; m < 4; ++m) _Pragma("unroll") for (int k = 0; k < 2; ++k) dst[m][k] = *(const PG8_LAS bf16x8*)(lds + PG8_SA(b, h) + aoff + m * 2048 + k * 1024); } while (0)
; #define PG8_LDB(dst, b, h) do { _Pragma("unroll") for (int n = 0; n < 2; ++n) _Pragma("unroll") for (int k = 0; k < 2; ++k) dst[n][k] = *(const PG8_LAS bf16x8*)(lds + PG8_SB(b, h) + boff + n * 2048 + k * 1024); } while (0)
; #define PG8_MMA(ai, bj, At, Bt) do { __builtin_amdgcn_s_setprio(1); _Pragma("unroll") for (int m = 0; m < 4; ++m) _Pragma("unroll") for (int n = 0; n < 2; ++n) _Pragma("unroll") for (int k = 0; k < 2; ++k) \
;         acc[ai][bj][m][n] = __builtin_amdgcn_mfma_f32_16x16x32_bf16(Bt[n][k], At[m][k], acc[ai][bj][m][n], 0, 0, 0); __builtin_amdgcn_s_setprio(0); } while (0)
; #define PG8_WAIT_V(n) asm volatile("s_waitcnt vmcnt(" #n ")" ::: "memory")
; #define PG8_WAIT_L(n) asm volatile("s_waitcnt lgkmcnt(" #n ")" ::: "memory")
; #define PG8_BAR __builtin_amdgcn_s_barrier()
; #define PG8_SCHED __builtin_amdgcn_sched_barrier(0)
; template <class Epi, class Sched, bool ALIGN_EPI = false, bool SP2 = false>
; __device__ __forceinline__ void gemm_phase(PG8_LAS unsigned char* lds, const Gemm g, const Sched& S, const Epi& E) {
;     ...
;         for (int t = 0; t < nt; t += 2) {
;             const bool last = (t == nt - 2);
;             const char* a1 = cA + (size_t)(t + 1) * kstep;
;             const char* a2 = last ? nA : cA + (size_t)(t + 2) * kstep; const char* b2 = last ? nB : cB + (size_t)(t + 2) * kstep;
;             const char* a3 = a2 + kstep; const char* b3 = b2 + kstep;
;             if (last && has_next) S.a_ready(nxt);
;             if constexpr (SP2) {
;             PG8_LDB(B0, 0, 0); PG8_LDB(B1, 0, 1); PG8_SCHED; PG8_LDA(At, 0, 0); PG8_STAGE(PG8_SA(1, 1), a1 + hstep, voffA);
;             PG8_WAIT_V(8); PG8_WAIT_L(0); PG8_BAR; PG8_MMA(0, 0, At, B0); PG8_MMA(0, 1, At, B1); PG8_BAR; PG8_SCHED;
.LBB0_643:
	s_cmp_lg_u32 s8, 0
	s_cbranch_scc1 .Lgemm_prio
	s_setprio 1

; #define PG8_STAGE(bufoff, gbase, voff) do { _Pragma("unroll") for (int _i = 0; _i < 2; ++_i) \
;         __builtin_amdgcn_global_load_lds((const unsigned*)((const char*)(gbase) + (voff)[_i]), (PG8_LAS unsigned*)(lds + (bufoff) + ldsw + _i * 8192), 16, 0, 0); } while (0)
; #define PG8_LDA(dst, b, h) do { _Pragma("unroll") for (int m = 0; m < 4; ++m) _Pragma("unroll") for (int k = 0; k < 2; ++k) dst[m][k] = *(const PG8_LAS bf16x8*)(lds + PG8_SA(b, h) + aoff + m * 2048 + k * 1024); } while (0)
; #define PG8_LDB(dst, b, h) do { _Pragma("unroll") for (int n = 0; n < 2; ++n) _Pragma("unroll") for (int k = 0; k < 2; ++k) dst[n][k] = *(const PG8_LAS bf16x8*)(lds + PG8_SB(b, h) + boff + n * 2048 + k * 1024); } while (0)
; #define PG8_MMA(ai, bj, At, Bt) do { __builtin_amdgcn_s_setprio(1); _Pragma("unroll") for (int m = 0; m < 4; ++m) _Pragma("unroll") for (int n = 0; n < 2; ++n) _Pragma("unroll") for (int k = 0; k < 2; ++k) \
;         acc[ai][bj][m][n] = __builtin_amdgcn_mfma_f32_16x16x32_bf16(Bt[n][k], At[m][k], acc[ai][bj][m][n], 0, 0, 0); __builtin_amdgcn_s_setprio(0); } while (0)
; #define PG8_WAIT_V(n) asm volatile("s_waitcnt vmcnt(" #n ")" ::: "memory")
; template <class Epi, class Sched, bool ALIGN_EPI = false, bool SP2 = false>
; __device__ __forceinline__ void gemm_phase(PG8_LAS unsigned char* lds, const Gemm g, const Sched& S, const Epi& E) {
;     ...
;             PG8_LDB(B0, 0, 0); PG8_LDB(B1, 0, 1); PG8_SCHED; PG8_LDA(At, 0, 0); PG8_STAGE(PG8_SA(1, 1), a1 + hstep, voffA);
;             PG8_WAIT_V(8); PG8_WAIT_L(0); PG8_BAR; PG8_MMA(0, 0, At, B0); PG8_MMA(0, 1, At, B1); PG8_BAR; PG8_SCHED;
;             PG8_LDA(At, 0, 1); PG8_STAGE(PG8_SB(0, 0), b2, voffB); PG8_STAGE(PG8_SB(0, 1), b2 + hstep, voffB); PG8_STAGE(PG8_SA(0, 0), a2, voffA);
;             PG8_WAIT_V(8); PG8_WAIT_L(0); PG8_BAR; PG8_MMA(1, 0, At, B0); PG8_MMA(1, 1, At, B1); PG8_BAR; PG8_SCHED;
;             PG8_LDB(B0, 1, 0); PG8_LDB(B1, 1, 1); PG8_SCHED; PG8_LDA(At, 1, 0); PG8_STAGE(PG8_SA(0, 1), a2 + hstep, voffA);
;             PG8_WAIT_V(8); PG8_WAIT_L(0); PG8_BAR; PG8_MMA(0, 0, At, B0); PG8_MMA(0, 1, At, B1); PG8_BAR; PG8_SCHED;
;             PG8_LDA(At, 1, 1); PG8_STAGE(PG8_SB(1, 0), b3, voffB); PG8_STAGE(PG8_SB(1, 1), b3 + hstep, voffB); PG8_STAGE(PG8_SA(1, 0), a3, voffA);
;             PG8_WAIT_V(8); PG8_WAIT_L(0); PG8_BAR; PG8_MMA(1, 0, At, B0); PG8_MMA(1, 1, At, B1); PG8_BAR; PG8_SCHED;
.LBB0_644:
	s_add_i32 s54, s10, 2
	s_add_u32 s20, vcc_lo, 0x80
	s_addc_u32 s11, vcc_hi, 0
	s_add_i32 s55, 0, 0x10000
	s_cmp_eq_u32 s2, s10
	s_cselect_b32 s11, s41, s11
	s_cselect_b32 s10, s40, s20
	s_cselect_b32 s21, s83, s13
	s_cselect_b32 s20, s82, s12
	s_add_i32 s64, 0, 0x14000
	v_add_u32_e32 v156, s55, v164
	v_add_u32_e32 v171, s64, v164
	ds_read_b128 v[144:147], v156
	ds_read_b128 v[148:151], v156 offset:1024
	ds_read_b128 v[152:155], v156 offset:2048
	ds_read_b128 v[156:159], v156 offset:3072
	ds_read_b128 v[160:163], v171
	ds_read_b128 v[190:193], v171 offset:1024
	ds_read_b128 v[194:197], v171 offset:2048
	ds_read_b128 v[198:201], v171 offset:3072
	v_lshl_add_u64 v[172:173], vcc, 0, v[142:143]
	s_add_i32 m0, s23, 0xc000
	ds_read_b128 v[202:205], v170
	ds_read_b128 v[206:209], v170 offset:1024
	ds_read_b128 v[210:213], v170 offset:2048
	ds_read_b128 v[214:217], v170 offset:3072
	ds_read_b128 v[218:221], v170 offset:4096
	ds_read_b128 v[222:225], v170 offset:5120
	ds_read_b128 v[226:229], v170 offset:6144
	ds_read_b128 v[230:233], v170 offset:7168
	global_load_lds_dwordx4 v[172:173], off
	v_lshl_add_u64 v[172:173], vcc, 0, v[140:141]
	s_add_i32 m0, s23, 0xe000
	s_nop 0
	global_load_lds_dwordx4 v[172:173], off
	s_waitcnt vmcnt(8)
	s_waitcnt lgkmcnt(0)
	s_barrier
	s_waitcnt lgkmcnt(0)
	v_mfma_f32_16x16x32_bf16 v[128:131], v[144:147], v[202:205], v[128:131]
	v_mfma_f32_16x16x32_bf16 v[124:127], v[152:155], v[202:205], v[124:127]
	v_mfma_f32_16x16x32_bf16 v[112:115], v[144:147], v[210:213], v[112:115]
	v_mfma_f32_16x16x32_bf16 v[108:111], v[152:155], v[210:213], v[108:111]
	v_mfma_f32_16x16x32_bf16 v[96:99], v[144:147], v[218:221], v[96:99]
	v_mfma_f32_16x16x32_bf16 v[92:95], v[152:155], v[218:221], v[92:95]
	v_mfma_f32_16x16x32_bf16 v[80:83], v[144:147], v[226:229], v[80:83]
	v_mfma_f32_16x16x32_bf16 v[76:79], v[152:155], v[226:229], v[76:79]
	v_mfma_f32_16x16x32_bf16 v[128:131], v[148:151], v[206:209], v[128:131]
	v_mfma_f32_16x16x32_bf16 v[124:127], v[156:159], v[206:209], v[124:127]
	v_mfma_f32_16x16x32_bf16 v[112:115], v[148:151], v[214:217], v[112:115]
	v_mfma_f32_16x16x32_bf16 v[108:111], v[156:159], v[214:217], v[108:111]
	v_mfma_f32_16x16x32_bf16 v[96:99], v[148:151], v[222:225], v[96:99]
	v_mfma_f32_16x16x32_bf16 v[92:95], v[156:159], v[222:225], v[92:95]
	v_mfma_f32_16x16x32_bf16 v[80:83], v[148:151], v[230:233], v[80:83]
	v_mfma_f32_16x16x32_bf16 v[76:79], v[156:159], v[230:233], v[76:79]
	v_mfma_f32_16x16x32_bf16 v[120:123], v[160:163], v[202:205], v[120:123]
	v_mfma_f32_16x16x32_bf16 v[116:119], v[194:197], v[202:205], v[116:119]
	v_mfma_f32_16x16x32_bf16 v[104:107], v[160:163], v[210:213], v[104:107]
	v_mfma_f32_16x16x32_bf16 v[100:103], v[194:197], v[210:213], v[100:103]
	v_mfma_f32_16x16x32_bf16 v[88:91], v[160:163], v[218:221], v[88:91]
	v_mfma_f32_16x16x32_bf16 v[84:87], v[194:197], v[218:221], v[84:87]
	v_mfma_f32_16x16x32_bf16 v[72:75], v[160:163], v[226:229], v[72:75]
	v_mfma_f32_16x16x32_bf16 v[68:71], v[194:197], v[226:229], v[68:71]
	v_mfma_f32_16x16x32_bf16 v[120:123], v[190:193], v[206:209], v[120:123]
	v_mfma_f32_16x16x32_bf16 v[116:119], v[198:201], v[206:209], v[116:119]
	v_mfma_f32_16x16x32_bf16 v[104:107], v[190:193], v[214:217], v[104:107]
	v_mfma_f32_16x16x32_bf16 v[100:103], v[198:201], v[214:217], v[100:103]
	v_mfma_f32_16x16x32_bf16 v[88:91], v[190:193], v[222:225], v[88:91]
	v_mfma_f32_16x16x32_bf16 v[84:87], v[198:201], v[222:225], v[84:87]
	v_mfma_f32_16x16x32_bf16 v[72:75], v[190:193], v[230:233], v[72:75]
	v_mfma_f32_16x16x32_bf16 v[68:71], v[198:201], v[230:233], v[68:71]
	s_barrier
	s_add_i32 s55, s55, s56
	v_lshl_add_u64 v[172:173], s[20:21], 0, v[138:139]
	s_mov_b32 m0, s55
	ds_read_b128 v[202:205], v170 offset:16384
	ds_read_b128 v[206:209], v170 offset:17408
	ds_read_b128 v[210:213], v170 offset:18432
	ds_read_b128 v[214:217], v170 offset:19456
	ds_read_b128 v[218:221], v170 offset:20480
	ds_read_b128 v[222:225], v170 offset:21504
	ds_read_b128 v[226:229], v170 offset:22528
	ds_read_b128 v[230:233], v170 offset:23552
	global_load_lds_dwordx4 v[172:173], off
	s_add_i32 m0, s55, 0x2000
	v_lshl_add_u64 v[234:235], s[20:21], 0, v[134:135]
	s_add_u32 s20, s20, s34
	s_addc_u32 s21, s21, 0
	s_add_i32 s55, s64, s56
	global_load_lds_dwordx4 v[234:235], off
	v_lshl_add_u64 v[236:237], s[20:21], 0, v[138:139]
	s_mov_b32 m0, s55
	v_lshl_add_u64 v[238:239], s[20:21], 0, v[134:135]
	global_load_lds_dwordx4 v[236:237], off
	s_add_i32 m0, s55, 0x2000
	v_lshl_add_u64 v[240:241], s[10:11], 0, v[136:137]
	global_load_lds_dwordx4 v[238:239], off
	s_mov_b32 m0, s23
	v_lshl_add_u64 v[242:243], s[10:11], 0, v[0:1]
	global_load_lds_dwordx4 v[240:241], off
	s_mov_b32 m0, s14
	s_nop 0
	global_load_lds_dwordx4 v[242:243], off
	s_waitcnt vmcnt(8)
	s_waitcnt lgkmcnt(0)
	s_barrier
; #define PG8_STAGE(bufoff, gbase, voff) do { _Pragma("unroll") for (int _i = 0; _i < 2; ++_i) \
;         __builtin_amdgcn_global_load_lds((const unsigned*)((const char*)(gbase) + (voff)[_i]), (PG8_LAS unsigned*)(lds + (bufoff) + ldsw + _i * 8192), 16, 0, 0); } while (0)
; #define PG8_LDA(dst, b, h) do { _Pragma("unroll") for (int m = 0; m < 4; ++m) _Pragma("unroll") for (int k = 0; k < 2; ++k) dst[m][k] = *(const PG8_LAS bf16x8*)(lds + PG8_SA(b, h) + aoff + m * 2048 + k * 1024); } while (0)
; #define PG8_LDB(dst, b, h) do { _Pragma("unroll") for (int n = 0; n < 2; ++n) _Pragma("unroll") for (int k = 0; k < 2; ++k) dst[n][k] = *(const PG8_LAS bf16x8*)(lds + PG8_SB(b, h) + boff + n * 2048 + k * 1024); } while (0)
; #define PG8_MMA(ai, bj, At, Bt) do { __builtin_amdgcn_s_setprio(1); _Pragma("unroll") for (int m = 0; m < 4; ++m) _Pragma("unroll") for (int n = 0; n < 2; ++n) _Pragma("unroll") for (int k = 0; k < 2; ++k) \
;         acc[ai][bj][m][n] = __builtin_amdgcn_mfma_f32_16x16x32_bf16(Bt[n][k], At[m][k], acc[ai][bj][m][n], 0, 0, 0); __builtin_amdgcn_s_setprio(0); } while (0)
; #define PG8_WAIT_V(n) asm volatile("s_waitcnt vmcnt(" #n ")" ::: "memory")
; #define PG8_WAIT_L(n) asm volatile("s_waitcnt lgkmcnt(" #n ")" ::: "memory")
; #define PG8_BAR __builtin_amdgcn_s_barrier()
; #define PG8_SCHED __builtin_amdgcn_sched_barrier(0)
; template <class Epi, class Sched, bool ALIGN_EPI = false, bool SP2 = false>
; __device__ __forceinline__ void gemm_phase(PG8_LAS unsigned char* lds, const Gemm g, const Sched& S, const Epi& E) {
;     ...
;             PG8_LDA(At, 0, 1); PG8_STAGE(PG8_SB(0, 0), b2, voffB); PG8_STAGE(PG8_SB(0, 1), b2 + hstep, voffB); PG8_STAGE(PG8_SA(0, 0), a2, voffA);
;             PG8_WAIT_V(8); PG8_WAIT_L(0); PG8_BAR; PG8_MMA(1, 0, At, B0); PG8_MMA(1, 1, At, B1); PG8_BAR; PG8_SCHED;
;             PG8_LDB(B0, 1, 0); PG8_LDB(B1, 1, 1); PG8_SCHED; PG8_LDA(At, 1, 0); PG8_STAGE(PG8_SA(0, 1), a2 + hstep, voffA);
;             PG8_WAIT_V(8); PG8_WAIT_L(0); PG8_BAR; PG8_MMA(0, 0, At, B0); PG8_MMA(0, 1, At, B1); PG8_BAR; PG8_SCHED;
;             PG8_LDA(At, 1, 1); PG8_STAGE(PG8_SB(1, 0), b3, voffB); PG8_STAGE(PG8_SB(1, 1), b3 + hstep, voffB); PG8_STAGE(PG8_SA(1, 0), a3, voffA);
;             PG8_WAIT_V(8); PG8_WAIT_L(0); PG8_BAR; PG8_MMA(1, 0, At, B0); PG8_MMA(1, 1, At, B1); PG8_BAR; PG8_SCHED;
	s_waitcnt lgkmcnt(0)
	v_mfma_f32_16x16x32_bf16 v[64:67], v[144:147], v[202:205], v[64:67]
	v_mfma_f32_16x16x32_bf16 v[60:63], v[152:155], v[202:205], v[60:63]
	v_mfma_f32_16x16x32_bf16 v[48:51], v[144:147], v[210:213], v[48:51]
	v_mfma_f32_16x16x32_bf16 v[44:47], v[152:155], v[210:213], v[44:47]
	v_mfma_f32_16x16x32_bf16 v[32:35], v[144:147], v[218:221], v[32:35]
	v_mfma_f32_16x16x32_bf16 v[28:31], v[152:155], v[218:221], v[28:31]
	v_mfma_f32_16x16x32_bf16 v[16:19], v[144:147], v[226:229], v[16:19]
	v_mfma_f32_16x16x32_bf16 v[12:15], v[152:155], v[226:229], v[12:15]
	v_mfma_f32_16x16x32_bf16 v[64:67], v[148:151], v[206:209], v[64:67]
	v_mfma_f32_16x16x32_bf16 v[60:63], v[156:159], v[206:209], v[60:63]
	v_mfma_f32_16x16x32_bf16 v[48:51], v[148:151], v[214:217], v[48:51]
	v_mfma_f32_16x16x32_bf16 v[44:47], v[156:159], v[214:217], v[44:47]
	v_mfma_f32_16x16x32_bf16 v[32:35], v[148:151], v[222:225], v[32:35]
	v_mfma_f32_16x16x32_bf16 v[28:31], v[156:159], v[222:225], v[28:31]
	v_mfma_f32_16x16x32_bf16 v[16:19], v[148:151], v[230:233], v[16:19]
	v_mfma_f32_16x16x32_bf16 v[12:15], v[156:159], v[230:233], v[12:15]
	v_mfma_f32_16x16x32_bf16 v[56:59], v[160:163], v[202:205], v[56:59]
	v_mfma_f32_16x16x32_bf16 v[52:55], v[194:197], v[202:205], v[52:55]
	v_mfma_f32_16x16x32_bf16 v[40:43], v[160:163], v[210:213], v[40:43]
	v_mfma_f32_16x16x32_bf16 v[36:39], v[194:197], v[210:213], v[36:39]
	v_mfma_f32_16x16x32_bf16 v[24:27], v[160:163], v[218:221], v[24:27]
	v_mfma_f32_16x16x32_bf16 v[20:23], v[194:197], v[218:221], v[20:23]
	v_mfma_f32_16x16x32_bf16 v[8:11], v[160:163], v[226:229], v[8:11]
	v_mfma_f32_16x16x32_bf16 v[4:7], v[194:197], v[226:229], v[4:7]
	v_mfma_f32_16x16x32_bf16 v[56:59], v[190:193], v[206:209], v[56:59]
	v_mfma_f32_16x16x32_bf16 v[52:55], v[198:201], v[206:209], v[52:55]
	v_mfma_f32_16x16x32_bf16 v[40:43], v[190:193], v[214:217], v[40:43]
	v_mfma_f32_16x16x32_bf16 v[36:39], v[198:201], v[214:217], v[36:39]
	v_mfma_f32_16x16x32_bf16 v[24:27], v[190:193], v[222:225], v[24:27]
	v_mfma_f32_16x16x32_bf16 v[20:23], v[198:201], v[222:225], v[20:23]
	v_mfma_f32_16x16x32_bf16 v[8:11], v[190:193], v[230:233], v[8:11]
	v_mfma_f32_16x16x32_bf16 v[4:7], v[198:201], v[230:233], v[4:7]
	s_barrier
	s_add_i32 s20, 0, 0x18000
	s_add_i32 s21, 0, 0x1c000
	v_add_u32_e32 v156, s20, v164
	v_add_u32_e32 v171, s21, v164
	ds_read_b128 v[144:147], v156
	ds_read_b128 v[148:151], v156 offset:1024
	ds_read_b128 v[152:155], v156 offset:2048
	ds_read_b128 v[156:159], v156 offset:3072
	ds_read_b128 v[160:163], v171
	ds_read_b128 v[190:193], v171 offset:1024
	ds_read_b128 v[194:197], v171 offset:2048
	ds_read_b128 v[198:201], v171 offset:3072
	s_add_u32 s10, s10, s34
	s_addc_u32 s11, s11, 0
	s_mov_b32 m0, s15
	v_lshl_add_u64 v[244:245], s[10:11], 0, v[136:137]
	ds_read_b128 v[202:205], v170 offset:32768
	ds_read_b128 v[206:209], v170 offset:33792
	ds_read_b128 v[210:213], v170 offset:34816
	ds_read_b128 v[214:217], v170 offset:35840
	ds_read_b128 v[218:221], v170 offset:36864
	ds_read_b128 v[222:225], v170 offset:37888
	ds_read_b128 v[226:229], v170 offset:38912
	ds_read_b128 v[230:233], v170 offset:39936
	global_load_lds_dwordx4 v[244:245], off
	v_lshl_add_u64 v[244:245], s[10:11], 0, v[0:1]
	s_mov_b32 m0, s77
	s_nop 0
	global_load_lds_dwordx4 v[244:245], off
	s_waitcnt vmcnt(8)
	s_waitcnt lgkmcnt(0)
	s_barrier
	s_waitcnt lgkmcnt(0)
	v_mfma_f32_16x16x32_bf16 v[128:131], v[144:147], v[202:205], v[128:131]
	v_mfma_f32_16x16x32_bf16 v[124:127], v[152:155], v[202:205], v[124:127]
	v_mfma_f32_16x16x32_bf16 v[112:115], v[144:147], v[210:213], v[112:115]
	v_mfma_f32_16x16x32_bf16 v[108:111], v[152:155], v[210:213], v[108:111]
	v_mfma_f32_16x16x32_bf16 v[96:99], v[144:147], v[218:221], v[96:99]
	v_mfma_f32_16x16x32_bf16 v[92:95], v[152:155], v[218:221], v[92:95]
	v_mfma_f32_16x16x32_bf16 v[80:83], v[144:147], v[226:229], v[80:83]
	v_mfma_f32_16x16x32_bf16 v[76:79], v[152:155], v[226:229], v[76:79]
	v_mfma_f32_16x16x32_bf16 v[128:131], v[148:151], v[206:209], v[128:131]
	v_mfma_f32_16x16x32_bf16 v[124:127], v[156:159], v[206:209], v[124:127]
	v_mfma_f32_16x16x32_bf16 v[112:115], v[148:151], v[214:217], v[112:115]
	v_mfma_f32_16x16x32_bf16 v[108:111], v[156:159], v[214:217], v[108:111]
	v_mfma_f32_16x16x32_bf16 v[96:99], v[148:151], v[222:225], v[96:99]
	v_mfma_f32_16x16x32_bf16 v[92:95], v[156:159], v[222:225], v[92:95]
	v_mfma_f32_16x16x32_bf16 v[80:83], v[148:151], v[230:233], v[80:83]
	v_mfma_f32_16x16x32_bf16 v[76:79], v[156:159], v[230:233], v[76:79]
	v_mfma_f32_16x16x32_bf16 v[120:123], v[160:163], v[202:205], v[120:123]
	v_mfma_f32_16x16x32_bf16 v[116:119], v[194:197], v[202:205], v[116:119]
	v_mfma_f32_16x16x32_bf16 v[104:107], v[160:163], v[210:213], v[104:107]
	v_mfma_f32_16x16x32_bf16 v[100:103], v[194:197], v[210:213], v[100:103]
	v_mfma_f32_16x16x32_bf16 v[88:91], v[160:163], v[218:221], v[88:91]
	v_mfma_f32_16x16x32_bf16 v[84:87], v[194:197], v[218:221], v[84:87]
	v_mfma_f32_16x16x32_bf16 v[72:75], v[160:163], v[226:229], v[72:75]
	v_mfma_f32_16x16x32_bf16 v[68:71], v[194:197], v[226:229], v[68:71]
	v_mfma_f32_16x16x32_bf16 v[120:123], v[190:193], v[206:209], v[120:123]
	v_mfma_f32_16x16x32_bf16 v[116:119], v[198:201], v[206:209], v[116:119]
	v_mfma_f32_16x16x32_bf16 v[104:107], v[190:193], v[214:217], v[104:107]
	v_mfma_f32_16x16x32_bf16 v[100:103], v[198:201], v[214:217], v[100:103]
	v_mfma_f32_16x16x32_bf16 v[88:91], v[190:193], v[222:225], v[88:91]
	v_mfma_f32_16x16x32_bf16 v[84:87], v[198:201], v[222:225], v[84:87]
	v_mfma_f32_16x16x32_bf16 v[72:75], v[190:193], v[230:233], v[72:75]
	v_mfma_f32_16x16x32_bf16 v[68:71], v[198:201], v[230:233], v[68:71]
	s_barrier
; #define PG8_STAGE(bufoff, gbase, voff) do { _Pragma("unroll") for (int _i = 0; _i < 2; ++_i) \
;         __builtin_amdgcn_global_load_lds((const unsigned*)((const char*)(gbase) + (voff)[_i]), (PG8_LAS unsigned*)(lds + (bufoff) + ldsw + _i * 8192), 16, 0, 0); } while (0)
; #define PG8_WAIT_V(n) asm volatile("s_waitcnt vmcnt(" #n ")" ::: "memory")
; #define PG8_BAR __builtin_amdgcn_s_barrier()
; template <class Epi, class Sched, bool ALIGN_EPI = false, bool SP2 = false>
; __device__ __forceinline__ void gemm_phase(PG8_LAS unsigned char* lds, const Gemm g, const Sched& S, const Epi& E) {
;     ...
;             PG8_LDB(B0, 1, 0); PG8_LDB(B1, 1, 1); PG8_SCHED; PG8_LDA(At, 1, 0); PG8_STAGE(PG8_SA(0, 1), a2 + hstep, voffA);
;             PG8_WAIT_V(8); PG8_WAIT_L(0); PG8_BAR; PG8_MMA(0, 0, At, B0); PG8_MMA(0, 1, At, B1); PG8_BAR; PG8_SCHED;
;             PG8_LDA(At, 1, 1); PG8_STAGE(PG8_SB(1, 0), b3, voffB); PG8_STAGE(PG8_SB(1, 1), b3 + hstep, voffB); PG8_STAGE(PG8_SA(1, 0), a3, voffA);
;             PG8_WAIT_V(8); PG8_WAIT_L(0); PG8_BAR; PG8_MMA(1, 0, At, B0); PG8_MMA(1, 1, At, B1); PG8_BAR; PG8_SCHED;
;             } else {
;             PG8_LDB(B0, 0, 0); PG8_SCHED; PG8_LDA(At, 0, 0); PG8_STAGE(PG8_SA(1, 1), a1 + hstep, voffA);
;             PG8_WAIT_L(8); PG8_BAR; PG8_WAIT_L(0); PG8_MMA(0, 0, At, B0); PG8_BAR; PG8_SCHED;
;             PG8_LDB(B1, 0, 1); PG8_STAGE(PG8_SB(0, 0), b2, voffB);
;             PG8_BAR; PG8_WAIT_L(0); PG8_MMA(0, 1, At, B1); PG8_BAR;
;             PG8_LDA(At, 0, 1); PG8_STAGE(PG8_SA(0, 0), a2, voffA);
;             PG8_BAR; PG8_WAIT_L(0); PG8_MMA(1, 0, At, B0); PG8_BAR; PG8_SCHED;
;             PG8_STAGE(PG8_SB(0, 1), b2 + hstep, voffB);
;             PG8_WAIT_V(6); PG8_BAR; PG8_MMA(1, 1, At, B1); PG8_BAR;
;             PG8_LDB(B0, 1, 0); PG8_SCHED; PG8_LDA(At, 1, 0); PG8_STAGE(PG8_SA(0, 1), a2 + hstep, voffA);
;             PG8_WAIT_L(8); PG8_BAR; PG8_WAIT_L(0); PG8_MMA(0, 0, At, B0); PG8_BAR; PG8_SCHED;
;             PG8_LDB(B1, 1, 1); PG8_STAGE(PG8_SB(1, 0), b3, voffB);
;             PG8_BAR; PG8_WAIT_L(0); PG8_MMA(0, 1, At, B1); PG8_BAR;
;             PG8_LDA(At, 1, 1); PG8_STAGE(PG8_SA(1, 0), a3, voffA);
;             PG8_BAR; PG8_WAIT_L(0); PG8_MMA(1, 0, At, B0); PG8_BAR; PG8_SCHED;
;             PG8_STAGE(PG8_SB(1, 1), b3 + hstep, voffB);
;             PG8_WAIT_V(6); PG8_BAR; PG8_MMA(1, 1, At, B1); PG8_BAR;
;             }
;         }
	s_add_i32 s10, s20, s56
	v_lshl_add_u64 v[172:173], v[172:173], 0, s[96:97]
	s_mov_b32 m0, s10
	ds_read_b128 v[202:205], v170 offset:49152
	ds_read_b128 v[206:209], v170 offset:50176
	ds_read_b128 v[210:213], v170 offset:51200
	ds_read_b128 v[214:217], v170 offset:52224
	ds_read_b128 v[218:221], v170 offset:53248
	ds_read_b128 v[222:225], v170 offset:54272
	ds_read_b128 v[226:229], v170 offset:55296
	ds_read_b128 v[230:233], v170 offset:56320
	global_load_lds_dwordx4 v[172:173], off
	v_lshl_add_u64 v[172:173], v[234:235], 0, s[96:97]
	s_add_i32 m0, s10, 0x2000
	s_add_i32 s10, s21, s56
	global_load_lds_dwordx4 v[172:173], off
	v_lshl_add_u64 v[172:173], v[236:237], 0, s[96:97]
	s_mov_b32 m0, s10
	s_nop 0
	global_load_lds_dwordx4 v[172:173], off
	v_lshl_add_u64 v[172:173], v[238:239], 0, s[96:97]
	s_add_i32 m0, s10, 0x2000
	s_nop 0
	global_load_lds_dwordx4 v[172:173], off
	v_lshl_add_u64 v[172:173], v[240:241], 0, s[96:97]
	s_mov_b32 m0, s1
	s_nop 0
	global_load_lds_dwordx4 v[172:173], off
	v_lshl_add_u64 v[172:173], v[242:243], 0, s[96:97]
	s_mov_b32 m0, s0
	s_nop 0
	global_load_lds_dwordx4 v[172:173], off
	s_waitcnt vmcnt(8)
	s_waitcnt lgkmcnt(0)
	s_barrier
	s_waitcnt lgkmcnt(0)
	v_mfma_f32_16x16x32_bf16 v[64:67], v[144:147], v[202:205], v[64:67]
	v_mfma_f32_16x16x32_bf16 v[60:63], v[152:155], v[202:205], v[60:63]
	v_mfma_f32_16x16x32_bf16 v[48:51], v[144:147], v[210:213], v[48:51]
	v_mfma_f32_16x16x32_bf16 v[44:47], v[152:155], v[210:213], v[44:47]
	v_mfma_f32_16x16x32_bf16 v[32:35], v[144:147], v[218:221], v[32:35]
	v_mfma_f32_16x16x32_bf16 v[28:31], v[152:155], v[218:221], v[28:31]
	v_mfma_f32_16x16x32_bf16 v[16:19], v[144:147], v[226:229], v[16:19]
	v_mfma_f32_16x16x32_bf16 v[12:15], v[152:155], v[226:229], v[12:15]
	v_mfma_f32_16x16x32_bf16 v[64:67], v[148:151], v[206:209], v[64:67]
	v_mfma_f32_16x16x32_bf16 v[60:63], v[156:159], v[206:209], v[60:63]
	v_mfma_f32_16x16x32_bf16 v[48:51], v[148:151], v[214:217], v[48:51]
	v_mfma_f32_16x16x32_bf16 v[44:47], v[156:159], v[214:217], v[44:47]
	v_mfma_f32_16x16x32_bf16 v[32:35], v[148:151], v[222:225], v[32:35]
	v_mfma_f32_16x16x32_bf16 v[28:31], v[156:159], v[222:225], v[28:31]
	v_mfma_f32_16x16x32_bf16 v[16:19], v[148:151], v[230:233], v[16:19]
	v_mfma_f32_16x16x32_bf16 v[12:15], v[156:159], v[230:233], v[12:15]
	v_mfma_f32_16x16x32_bf16 v[56:59], v[160:163], v[202:205], v[56:59]
	v_mfma_f32_16x16x32_bf16 v[52:55], v[194:197], v[202:205], v[52:55]
	v_mfma_f32_16x16x32_bf16 v[40:43], v[160:163], v[210:213], v[40:43]
	v_mfma_f32_16x16x32_bf16 v[36:39], v[194:197], v[210:213], v[36:39]
	v_mfma_f32_16x16x32_bf16 v[24:27], v[160:163], v[218:221], v[24:27]
	v_mfma_f32_16x16x32_bf16 v[20:23], v[194:197], v[218:221], v[20:23]
	v_mfma_f32_16x16x32_bf16 v[8:11], v[160:163], v[226:229], v[8:11]
	v_mfma_f32_16x16x32_bf16 v[4:7], v[194:197], v[226:229], v[4:7]
	v_mfma_f32_16x16x32_bf16 v[56:59], v[190:193], v[206:209], v[56:59]
	v_mfma_f32_16x16x32_bf16 v[52:55], v[198:201], v[206:209], v[52:55]
	v_mfma_f32_16x16x32_bf16 v[40:43], v[190:193], v[214:217], v[40:43]
	v_mfma_f32_16x16x32_bf16 v[36:39], v[198:201], v[214:217], v[36:39]
	v_mfma_f32_16x16x32_bf16 v[24:27], v[190:193], v[222:225], v[24:27]
	v_mfma_f32_16x16x32_bf16 v[20:23], v[198:201], v[222:225], v[20:23]
	v_mfma_f32_16x16x32_bf16 v[8:11], v[190:193], v[230:233], v[8:11]
	v_mfma_f32_16x16x32_bf16 v[4:7], v[198:201], v[230:233], v[4:7]
	s_barrier
	s_add_u32 s12, s12, 0x100
	s_addc_u32 s13, s13, 0
	s_add_u32 vcc_lo, vcc_lo, 0x100
	s_addc_u32 vcc_hi, vcc_hi, 0
	s_cmp_ge_u32 s54, s94
	s_mov_b32 s10, s54
	s_cbranch_scc0 .LBB0_644
	s_setprio 0
	s_and_b64 vcc, exec, s[8:9]
	s_cbranch_vccz .LBB0_647
	s_barrier
